# prep phase: second round of adaLN partial items (512..767) handled by blocks 256..511 instead of blocks 0..255 (which keep the S5 derived parameters), 512-block grid only
# speedup vs baseline: 1.0159x; 1.0017x over previous
.LBB0_55:
	v_lshl_add_u64 v[32:33], v[18:19], 0, s[6:7]
	v_add_co_u32_e32 v44, vcc, s9, v32
	global_load_dwordx4 v[28:31], v[32:33], off
	s_nop 0
	v_addc_co_u32_e32 v45, vcc, 0, v33, vcc
	v_add_co_u32_e32 v46, vcc, s10, v32
	s_add_u32 s6, s6, 0x18000
	s_nop 0
	v_addc_co_u32_e32 v47, vcc, 0, v33, vcc
	v_add_co_u32_e32 v48, vcc, s11, v32
	s_addc_u32 s7, s7, 0
	s_nop 0
	v_addc_co_u32_e32 v49, vcc, 0, v33, vcc
	global_load_dwordx4 v[32:35], v[44:45], off
	global_load_dwordx4 v[36:39], v[46:47], off
	global_load_dwordx4 v[40:43], v[48:49], off
	ds_read_b128 v[44:47], v26
	ds_read_b128 v[48:51], v26 offset:256
	ds_read_b128 v[52:55], v26 offset:512
	v_add_u32_e32 v26, 16, v26
	s_cmp_eq_u32 s6, 0x60000
	s_waitcnt lgkmcnt(0)
	v_mov_b32_e32 v56, v47
	s_waitcnt lgkmcnt(1)
	v_mov_b32_e32 v58, v51
	s_waitcnt lgkmcnt(0)
	v_mov_b32_e32 v60, v55
	s_waitcnt vmcnt(0)
	v_pk_fma_f32 v[0:1], v[44:45], v[28:29], v[0:1] op_sel_hi:[0,1,1]
	v_pk_fma_f32 v[2:3], v[44:45], v[30:31], v[2:3] op_sel_hi:[0,1,1]
	v_pk_fma_f32 v[8:9], v[28:29], v[48:49], v[8:9] op_sel_hi:[1,0,1]
	v_pk_fma_f32 v[10:11], v[30:31], v[48:49], v[10:11] op_sel_hi:[1,0,1]
	v_pk_fma_f32 v[4:5], v[28:29], v[52:53], v[4:5] op_sel_hi:[1,0,1]
	v_pk_fma_f32 v[6:7], v[30:31], v[52:53], v[6:7] op_sel_hi:[1,0,1]
	s_waitcnt vmcnt(2)
	v_pk_fma_f32 v[0:1], v[44:45], v[32:33], v[0:1] op_sel:[1,0,0]
	v_pk_fma_f32 v[2:3], v[44:45], v[34:35], v[2:3] op_sel:[1,0,0]
	v_pk_fma_f32 v[8:9], v[32:33], v[48:49], v[8:9] op_sel:[0,1,0]
	v_pk_fma_f32 v[10:11], v[34:35], v[48:49], v[10:11] op_sel:[0,1,0]
	v_pk_fma_f32 v[4:5], v[32:33], v[52:53], v[4:5] op_sel:[0,1,0]
	v_pk_fma_f32 v[6:7], v[34:35], v[52:53], v[6:7] op_sel:[0,1,0]
	s_waitcnt vmcnt(1)
	v_pk_fma_f32 v[0:1], v[46:47], v[36:37], v[0:1] op_sel_hi:[0,1,1]
	v_pk_fma_f32 v[2:3], v[46:47], v[38:39], v[2:3] op_sel_hi:[0,1,1]
	v_pk_fma_f32 v[8:9], v[36:37], v[50:51], v[8:9] op_sel_hi:[1,0,1]
	v_pk_fma_f32 v[10:11], v[38:39], v[50:51], v[10:11] op_sel_hi:[1,0,1]
	v_pk_fma_f32 v[4:5], v[36:37], v[54:55], v[4:5] op_sel_hi:[1,0,1]
	v_pk_fma_f32 v[6:7], v[38:39], v[54:55], v[6:7] op_sel_hi:[1,0,1]
	s_waitcnt vmcnt(0)
	v_pk_fma_f32 v[0:1], v[56:57], v[40:41], v[0:1] op_sel_hi:[0,1,1]
	v_pk_fma_f32 v[2:3], v[56:57], v[42:43], v[2:3] op_sel_hi:[0,1,1]
	v_pk_fma_f32 v[8:9], v[40:41], v[58:59], v[8:9] op_sel_hi:[1,0,1]
	v_pk_fma_f32 v[10:11], v[42:43], v[58:59], v[10:11] op_sel_hi:[1,0,1]
	v_pk_fma_f32 v[4:5], v[40:41], v[60:61], v[4:5] op_sel_hi:[1,0,1]
	v_pk_fma_f32 v[6:7], v[42:43], v[60:61], v[6:7] op_sel_hi:[1,0,1]
	s_cbranch_scc0 .LBB0_55
	ds_write_b128 v22, v[0:3] offset:768
	ds_write_b128 v22, v[8:11] offset:1792
	ds_write_b128 v22, v[4:7] offset:2816
	s_waitcnt lgkmcnt(0)
	s_barrier
	ds_read_b32 v2, v20 offset:768
	ds_read_b32 v3, v20 offset:3840
	ds_read_b32 v4, v20 offset:6912
	ds_read_b32 v5, v20 offset:9984
	s_lshl_b32 s6, s14, 1
	s_add_i32 s6, s6, s15
	s_waitcnt lgkmcnt(2)
	v_add_f32_e32 v2, v2, v3
	s_mul_i32 s6, s6, 3
	v_lshl_add_u64 v[0:1], s[0:1], 2, v[16:17]
	s_waitcnt lgkmcnt(1)
	v_add_f32_e32 v2, v2, v4
	s_waitcnt lgkmcnt(0)
	v_add_f32_e32 v2, v2, v5
	v_mad_i64_i32 v[0:1], s[0:1], s6, v25, v[0:1]
	flat_store_dword v[0:1], v2
	ds_read_b32 v2, v20 offset:1792
	ds_read_b32 v3, v20 offset:4864
	ds_read_b32 v4, v20 offset:7936
	ds_read_b32 v5, v20 offset:11008
	s_cmp_eq_u32 s82, 0x200
	s_cbranch_scc0 .Lad_gen
	s_add_i32 s8, s8, 0x100
	s_cmpk_lt_u32 s76, 0x100
	s_cselect_b32 s8, 0x300, s8
	s_branch .Lad_go
.Lad_gen:
	s_add_i32 s8, s8, s82
.Lad_go:
	s_cmpk_gt_i32 s8, 0x2ff
	s_waitcnt lgkmcnt(0)
	v_add_f32_e32 v2, v2, v3
	v_add_f32_e32 v2, v2, v4
	v_add_f32_e32 v4, v2, v5
	v_add_co_u32_e32 v2, vcc, s9, v0
	s_nop 1
	v_addc_co_u32_e32 v3, vcc, 0, v1, vcc
	flat_store_dword v[2:3], v4
	ds_read_b32 v2, v20 offset:2816
	ds_read_b32 v3, v20 offset:5888
	ds_read_b32 v4, v20 offset:8960
	ds_read_b32 v5, v20 offset:12032
	v_add_co_u32_e32 v0, vcc, 0xc000, v0
	s_waitcnt lgkmcnt(0)
	v_add_f32_e32 v2, v2, v3
	v_add_f32_e32 v2, v2, v4
	v_add_f32_e32 v2, v2, v5
	v_addc_co_u32_e32 v1, vcc, 0, v1, vcc
	flat_store_dword v[0:1], v2
	s_waitcnt lgkmcnt(0)
	s_barrier
	s_cbranch_scc0 .LBB0_52
